# chunk-0 row-sum adds moved out of the QK tail (before the first PV MFMA) into the PV shadows of gaps 12-15
# baseline (speedup 1.0000x reference)
; DI int fresh_tid() { int t = threadIdx.x; asm volatile("" : "+v"(t)); return t; }
; DI float bf2f(unsigned v) { return __uint_as_float(v << 16); }
; DI f32x16 zero16() { f32x16 z; for (int i = 0; i < 16; ++i) z[i] = 0.f; return z; }
; DI void attn_item(const P& p, int l, int item, char* smem) {
;     ...
;   const int tid = fresh_tid(), lane = tid & 63, wave = tid >> 6;
;   const int li = lane & 31, g = lane >> 5;
;   const int qg = wave & 3, c = wave >> 2;
;   const int bh = item & 7, qb = (item >> 8) * 32 + ((item & 255) >> 3);
;   const int b = bh >> 2, h = bh & 3;
;   const float lam_init = (l == 0) ? 0.2f : 0.35550906759096926f;
;   float lam;
;   {
;     float s1 = p.lq1[l * 64 + lane] * p.lk1[l * 64 + lane];
;     float s2 = p.lq2[l * 64 + lane] * p.lk2[l * 64 + lane];
; #pragma unroll
;     for (int m = 32; m >= 1; m >>= 1) { s1 += __shfl_xor(s1, m); s2 += __shfl_xor(s2, m); }
;     lam = __expf(s1) - __expf(s2) + lam_init;
;   }
;   const int tq = qb * 128 + qg * 32 + li;
;   bf16x8 qf[4];
;   float negm;
;   {
;     float q2 = 0.f;
; #pragma unroll
;     for (int ks = 0; ks < 4; ++ks) {
;       qf[ks] = *(const bf16x8*)(p.Qb + ((size_t)((bh * 2 + c) * SEQ + tq)) * 64 + 16 * ks + 8 * g);
; #pragma unroll
;       for (int j = 0; j < 8; ++j) { const float v = bf2f((unsigned)(u16)qf[ks][j]); q2 += v * v; }
;     }
;     q2 += __shfl_xor(q2, 32);
;     const float k2 = __uint_as_float(p.kmax[bh * 2 + c]);
;     negm = -(sqrtf(q2 * k2) * 1.01f + 1e-3f);
;   }
;   f32x16 O[4];
; #pragma unroll
;   for (int eb = 0; eb < 4; ++eb) O[eb] = zero16();
;   float ls = 0.f;
;   u32x4 kreg[2], vreg[2];
;   const u16* kbase = p.Kb + (size_t)(bh * 2) * SEQ * 64;
;   const u16* vbase = p.VT + (size_t)(bh * 128) * VTP;
; #pragma unroll
;   for (int i = 0; i < 2; ++i) kreg[i] = *(const u32x4*)(kbase + ((size_t)i * SEQ) * 64 + tid * 8);
; #pragma unroll
;   for (int i = 0; i < 2; ++i) {
;     const int cid = tid + NT * i;
;     const int e = cid >> 3, kc = cid & 7;
;     vreg[i] = *(const u32x4*)(vbase + (size_t)e * VTP + kc * 8);
;   }
.LBB0_465:
	v_mov_b32_e32 v161, v198
	v_readlane_b32 s6, v248, 26
	v_and_b32_e32 v141, 63, v161
	v_readlane_b32 s72, v248, 30
	v_or_b32_e32 v188, s6, v141
	v_lshlrev_b64 v[0:1], 2, v[188:189]
	v_lshl_add_u64 v[2:3], s[22:23], 0, v[0:1]
	global_load_dword v4, v[2:3], off
	v_lshl_add_u64 v[2:3], s[24:25], 0, v[0:1]
	v_readlane_b32 s73, v248, 31
	global_load_dword v5, v[2:3], off
	v_lshl_add_u64 v[2:3], s[26:27], 0, v[0:1]
	v_lshl_add_u64 v[0:1], s[72:73], 0, v[0:1]
	global_load_dword v2, v[2:3], off
	v_and_b32_e32 v3, 64, v215
	global_load_dword v0, v[0:1], off
	v_add_u32_e32 v3, 64, v3
	v_xor_b32_e32 v7, 32, v215
	v_cmp_lt_i32_e32 vcc, v7, v3
	v_bfe_u32 v162, v161, 6, 2
	s_lshl_b32 s6, s95, 4
	v_cndmask_b32_e32 v7, v215, v7, vcc
	v_lshlrev_b32_e32 v158, 2, v7
	v_ashrrev_i32_e32 v160, 8, v161
	v_and_b32_e32 v17, 31, v161
	s_and_b32 s12, s95, 7
	s_and_b32 s6, s6, 0xffffff80
	v_bfe_u32 v159, v161, 5, 1
	v_lshlrev_b32_e32 v188, 4, v159
	s_and_b32 s13, s64, 7
	s_lshl_b32 s11, s13, 21
	v_mov_b32_e32 v143, v189
	v_ashrrev_i32_e32 v24, 3, v161
	s_movk_i32 s14, 0x4080
	v_mul_lo_u32 v170, v24, s94
	v_mov_b32_e32 v167, 0
	s_mov_b32 s10, 0
	v_mul_u32_u24_e32 v174, 0x90, v17
	v_lshlrev_b32_e32 v8, 5, v162
	v_or3_b32 v140, v8, s6, v17
	s_lshl_b32 s6, s12, 14
	v_lshlrev_b32_e32 v8, 13, v160
	v_add3_u32 v8, v8, s6, v140
	v_ashrrev_i32_e32 v9, 31, v8
	v_lshlrev_b64 v[8:9], 7, v[8:9]
	v_lshl_add_u64 v[8:9], s[38:39], 0, v[8:9]
	v_lshl_add_u64 v[8:9], v[8:9], 0, v[188:189]
	global_load_dwordx4 v[112:115], v[8:9], off
	global_load_dwordx4 v[116:119], v[8:9], off offset:32
	global_load_dwordx4 v[124:127], v[8:9], off offset:64
	global_load_dwordx4 v[120:123], v[8:9], off offset:96
	v_readlane_b32 s6, v248, 38
	v_readlane_b32 s7, v248, 39
	v_lshl_add_u32 v14, s12, 1, v160
	v_ashrrev_i32_e32 v15, 31, v14
	v_lshl_add_u64 v[14:15], v[14:15], 2, s[6:7]
	global_load_dword v14, v[14:15], off
	s_lshl_b32 s6, s12, 21
	s_add_u32 s6, s40, s6
	v_lshlrev_b32_e32 v10, 3, v161
	v_ashrrev_i32_e32 v11, 31, v10
	s_addc_u32 s7, s41, 0
	v_lshlrev_b64 v[32:33], 1, v[10:11]
	v_lshl_add_u64 v[22:23], s[6:7], 0, v[32:33]
	s_mul_i32 s6, s12, 0x204000
	s_add_u32 s6, s42, s6
	v_and_b32_e32 v11, 56, v10
	s_addc_u32 s7, s43, 0
	v_lshlrev_b32_e32 v142, 1, v11
	v_add_u32_e32 v11, 0x200, v161
	v_lshl_add_u64 v[12:13], s[6:7], 0, v[142:143]
	v_ashrrev_i32_e32 v25, 3, v11
	v_mad_i64_i32 v[34:35], s[6:7], v24, s14, 0
	v_mad_i64_i32 v[36:37], s[6:7], v25, s14, 0
	v_mad_i64_i32 v[18:19], s[6:7], v25, s14, v[12:13]
	v_mad_i64_i32 v[20:21], s[6:7], v24, s14, v[12:13]
	s_mov_b32 s6, 0x100000
	s_nop 0
	v_add_co_u32_e32 v8, vcc, s6, v22
	v_and_b32_e32 v26, 48, v10
	v_lshlrev_b32_e32 v10, 2, v161
	v_addc_co_u32_e32 v9, vcc, 0, v23, vcc
	v_and_b32_e32 v27, 4, v10
	global_load_dwordx4 v[80:83], v[18:19], off
	global_load_dwordx4 v[84:87], v[20:21], off
	s_nop 0
	global_load_dwordx4 v[88:91], v[8:9], off
	s_nop 0
	global_load_dwordx4 v[92:95], v[22:23], off
	v_mov_b32_e32 v38, v167
	v_mov_b32_e32 v39, v167
	v_mov_b32_e32 v40, v167
	v_mov_b32_e32 v41, v167
	v_mov_b32_e32 v42, v167
	v_mov_b32_e32 v43, v167
	v_mov_b32_e32 v44, v167
	v_mov_b32_e32 v45, v167
	v_mov_b32_e32 v46, v167
	v_mov_b32_e32 v47, v167
	v_mov_b32_e32 v48, 0
	v_mov_b32_e32 v49, v167
	v_mov_b32_e32 v50, v167
	v_mov_b32_e32 v51, v167
	v_mov_b32_e32 v52, v167
	v_mov_b32_e32 v53, v167
	v_mov_b32_e32 v54, v167
	v_mov_b32_e32 v55, v167
	v_mov_b32_e32 v56, v167
	v_mov_b32_e32 v57, v167
	v_mov_b32_e32 v58, v167
	v_mov_b32_e32 v59, v167
	v_mov_b32_e32 v60, v167
	v_mov_b32_e32 v61, v167
	v_mov_b32_e32 v62, v167
	v_mov_b32_e32 v63, v167
	v_mov_b32_e32 v64, 0
	v_mov_b32_e32 v65, v167
	v_mov_b32_e32 v66, v167
	v_mov_b32_e32 v67, v167
	v_mov_b32_e32 v68, v167
	v_mov_b32_e32 v69, v167
	v_mov_b32_e32 v70, v167
	v_mov_b32_e32 v71, v167
	v_mov_b32_e32 v72, v167
	v_mov_b32_e32 v73, v167
	v_mov_b32_e32 v74, v167
	v_mov_b32_e32 v75, v167
	v_mov_b32_e32 v76, v167
	v_mov_b32_e32 v77, v167
	v_mov_b32_e32 v78, v167
	v_mov_b32_e32 v79, v167
	v_readlane_b32 s74, v248, 32
	v_readlane_b32 s75, v248, 33
	s_waitcnt vmcnt(11)
	v_mul_f32_e32 v6, v4, v5
	ds_bpermute_b32 v6, v158, v6
	s_waitcnt vmcnt(9)
	v_mul_f32_e32 v1, v2, v0
	ds_bpermute_b32 v1, v158, v1
	s_waitcnt lgkmcnt(1)
	v_fmac_f32_e32 v6, v4, v5
	s_waitcnt lgkmcnt(0)
	v_fmac_f32_e32 v1, v2, v0
	v_xor_b32_e32 v0, 16, v215
	v_cmp_lt_i32_e32 vcc, v0, v3
	s_nop 1
	v_cndmask_b32_e32 v0, v215, v0, vcc
	v_lshlrev_b32_e32 v0, 2, v0
	ds_bpermute_b32 v2, v0, v6
	ds_bpermute_b32 v0, v0, v1
	s_waitcnt lgkmcnt(1)
	v_add_f32_e32 v2, v6, v2
	s_waitcnt lgkmcnt(0)
	v_add_f32_e32 v0, v1, v0
	v_xor_b32_e32 v1, 8, v215
	v_cmp_lt_i32_e32 vcc, v1, v3
	s_nop 1
	v_cndmask_b32_e32 v1, v215, v1, vcc
	v_lshlrev_b32_e32 v1, 2, v1
	ds_bpermute_b32 v4, v1, v2
	ds_bpermute_b32 v1, v1, v0
	s_waitcnt lgkmcnt(1)
	v_add_f32_e32 v2, v2, v4
	s_waitcnt lgkmcnt(0)
	v_add_f32_e32 v0, v0, v1
	v_xor_b32_e32 v1, 4, v215
	v_cmp_lt_i32_e32 vcc, v1, v3
	s_nop 1
	v_cndmask_b32_e32 v1, v215, v1, vcc
	v_lshlrev_b32_e32 v1, 2, v1
	ds_bpermute_b32 v4, v1, v2
	ds_bpermute_b32 v1, v1, v0
	s_waitcnt lgkmcnt(1)
	v_add_f32_e32 v2, v2, v4
	s_waitcnt lgkmcnt(0)
	v_add_f32_e32 v0, v0, v1
	v_xor_b32_e32 v1, 2, v215
	v_cmp_lt_i32_e32 vcc, v1, v3
	s_nop 1
	v_cndmask_b32_e32 v1, v215, v1, vcc
	v_lshlrev_b32_e32 v1, 2, v1
	ds_bpermute_b32 v4, v1, v2
	ds_bpermute_b32 v1, v1, v0
	s_waitcnt lgkmcnt(1)
	v_add_f32_e32 v163, v2, v4
	s_waitcnt lgkmcnt(0)
	v_add_f32_e32 v165, v0, v1
	v_xor_b32_e32 v0, 1, v215
	v_cmp_lt_i32_e32 vcc, v0, v3
	s_nop 1
	v_cndmask_b32_e32 v0, v215, v0, vcc
	v_lshlrev_b32_e32 v0, 2, v0
	ds_bpermute_b32 v164, v0, v163
	ds_bpermute_b32 v166, v0, v165
	s_waitcnt vmcnt(8)
; DI float bf2f(unsigned v) { return __uint_as_float(v << 16); }
; DI f32x16 zero16() { f32x16 z; for (int i = 0; i < 16; ++i) z[i] = 0.f; return z; }
; DI void attn_item(const P& p, int l, int item, char* smem) {
;     ...
;     float q2 = 0.f;
; #pragma unroll
;     for (int ks = 0; ks < 4; ++ks) {
;       qf[ks] = *(const bf16x8*)(p.Qb + ((size_t)((bh * 2 + c) * SEQ + tq)) * 64 + 16 * ks + 8 * g);
; #pragma unroll
;       for (int j = 0; j < 8; ++j) { const float v = bf2f((unsigned)(u16)qf[ks][j]); q2 += v * v; }
;     }
;     q2 += __shfl_xor(q2, 32);
;     const float k2 = __uint_as_float(p.kmax[bh * 2 + c]);
;     negm = -(sqrtf(q2 * k2) * 1.01f + 1e-3f);
;   }
;   f32x16 O[4];
; #pragma unroll
;   for (int eb = 0; eb < 4; ++eb) O[eb] = zero16();
;   float ls = 0.f;
;   u32x4 kreg[2], vreg[2];
;   const u16* kbase = p.Kb + (size_t)(bh * 2) * SEQ * 64;
;   const u16* vbase = p.VT + (size_t)(bh * 128) * VTP;
; #pragma unroll
;   for (int i = 0; i < 2; ++i) kreg[i] = *(const u32x4*)(kbase + ((size_t)i * SEQ) * 64 + tid * 8);
; #pragma unroll
;   for (int i = 0; i < 2; ++i) {
;     const int cid = tid + NT * i;
;     const int e = cid >> 3, kc = cid & 7;
;     vreg[i] = *(const u32x4*)(vbase + (size_t)e * VTP + kc * 8);
;   }
;   for (int kt = -1; kt < 128; ++kt) {
;     if (kt + 1 < 128) {
;       u16* Kd = Ks + ((kt + 1) & 1) * (256 * 72);
;       u16* Vd = Kd + 2 * 64 * 72;
; #pragma unroll
;       for (int i = 0; i < 2; ++i) {
;         const int row = tid >> 3, kc = tid & 7;
;         *(u32x4*)(Kd + (i * 64 + row) * 72 + kc * 8) = kreg[i];
;       }
; #pragma unroll
;       for (int i = 0; i < 2; ++i) {
;         const int cid = tid + NT * i;
;         const int e = cid >> 3, kc = cid & 7;
;         uint2 w0; w0.x = vreg[i][0]; w0.y = vreg[i][1];
;         uint2 w1; w1.x = vreg[i][2]; w1.y = vreg[i][3];
;         u16* vd = Vd + e * 72 + (kc >> 1) * 16 + (kc & 1) * 4;
;         *(uint2*)vd = w0;
;         *(uint2*)(vd + 8) = w1;
;       }
;     }
;     if (kt + 2 < 128) {
;       const int kn = kt + 2;
; #pragma unroll
;       for (int i = 0; i < 2; ++i) kreg[i] = *(const u32x4*)(kbase + ((size_t)i * SEQ + kn * 64) * 64 + tid * 8);
; #pragma unroll
;       for (int i = 0; i < 2; ++i) {
;         const int cid = tid + NT * i;
;         const int e = cid >> 3, kc = cid & 7;
;         vreg[i] = *(const u32x4*)(vbase + (size_t)e * VTP + kn * 64 + kc * 8);
;       }
	v_and_b32_e32 v3, 0xffff0000, v112
	v_lshlrev_b32_e32 v2, 16, v112
	v_mul_f32_e32 v3, v3, v3
	v_fmac_f32_e32 v3, v2, v2
	v_lshlrev_b32_e32 v2, 16, v113
	v_fmac_f32_e32 v3, v2, v2
	v_and_b32_e32 v2, 0xffff0000, v113
	v_fmac_f32_e32 v3, v2, v2
	v_lshlrev_b32_e32 v2, 16, v114
	v_fmac_f32_e32 v3, v2, v2
	v_and_b32_e32 v2, 0xffff0000, v114
	v_fmac_f32_e32 v3, v2, v2
	v_lshlrev_b32_e32 v2, 16, v115
	v_fmac_f32_e32 v3, v2, v2
	v_and_b32_e32 v2, 0xffff0000, v115
	v_fmac_f32_e32 v3, v2, v2
	s_waitcnt vmcnt(7)
	v_lshlrev_b32_e32 v2, 16, v116
	v_fmac_f32_e32 v3, v2, v2
	v_and_b32_e32 v2, 0xffff0000, v116
	v_fmac_f32_e32 v3, v2, v2
	v_lshlrev_b32_e32 v2, 16, v117
	v_fmac_f32_e32 v3, v2, v2
	v_and_b32_e32 v2, 0xffff0000, v117
	v_fmac_f32_e32 v3, v2, v2
	v_lshlrev_b32_e32 v2, 16, v118
	v_fmac_f32_e32 v3, v2, v2
	v_and_b32_e32 v2, 0xffff0000, v118
	v_fmac_f32_e32 v3, v2, v2
	v_lshlrev_b32_e32 v2, 16, v119
	v_fmac_f32_e32 v3, v2, v2
	v_and_b32_e32 v2, 0xffff0000, v119
	v_fmac_f32_e32 v3, v2, v2
	s_waitcnt vmcnt(6)
	v_lshlrev_b32_e32 v2, 16, v124
	v_fmac_f32_e32 v3, v2, v2
	v_and_b32_e32 v2, 0xffff0000, v124
	v_fmac_f32_e32 v3, v2, v2
	v_lshlrev_b32_e32 v2, 16, v125
	v_fmac_f32_e32 v3, v2, v2
	v_and_b32_e32 v2, 0xffff0000, v125
	v_fmac_f32_e32 v3, v2, v2
	v_lshlrev_b32_e32 v2, 16, v126
	v_fmac_f32_e32 v3, v2, v2
	v_and_b32_e32 v2, 0xffff0000, v126
	v_fmac_f32_e32 v3, v2, v2
	v_lshlrev_b32_e32 v2, 16, v127
	v_fmac_f32_e32 v3, v2, v2
	v_and_b32_e32 v2, 0xffff0000, v127
	v_fmac_f32_e32 v3, v2, v2
	s_waitcnt vmcnt(5)
	v_lshlrev_b32_e32 v0, 16, v120
	v_fmac_f32_e32 v3, v0, v0
	v_and_b32_e32 v0, 0xffff0000, v120
	v_fmac_f32_e32 v3, v0, v0
	v_and_b32_e32 v1, 0xffff0000, v121
	v_lshlrev_b32_e32 v0, 16, v121
	v_pk_mul_f32 v[0:1], v[0:1], v[0:1]
	s_nop 0
	v_add_f32_e32 v0, v0, v3
	v_add_f32_e32 v2, v1, v0
	v_and_b32_e32 v1, 0xffff0000, v122
	v_lshlrev_b32_e32 v0, 16, v122
	v_pk_mul_f32 v[0:1], v[0:1], v[0:1]
	s_nop 0
	v_add_f32_e32 v0, v0, v2
	v_add_f32_e32 v2, v1, v0
	v_and_b32_e32 v1, 0xffff0000, v123
	v_lshlrev_b32_e32 v0, 16, v123
	v_pk_mul_f32 v[0:1], v[0:1], v[0:1]
	s_nop 0
	v_add_f32_e32 v0, v0, v2
	v_add_f32_e32 v0, v1, v0
	ds_bpermute_b32 v1, v158, v0
	s_waitcnt lgkmcnt(0)
	v_add_f32_e32 v2, v0, v1
	s_mov_b32 s6, 0xf800000
	s_waitcnt vmcnt(4)
	v_mul_f32_e32 v0, v14, v2
	v_cmp_gt_f32_e32 vcc, s6, v0
	v_mul_f32_e32 v1, 0x4f800000, v0
	s_nop 0
	v_cndmask_b32_e32 v0, v0, v1, vcc
	v_sqrt_f32_e32 v1, v0
	s_nop 0
	v_add_u32_e32 v2, -1, v1
	v_fma_f32 v3, -v2, v1, v0
	v_cmp_ge_f32_e64 s[6:7], 0, v3
	v_add_u32_e32 v3, 1, v1
	s_nop 0
	v_cndmask_b32_e64 v2, v1, v2, s[6:7]
	v_fma_f32 v1, -v3, v1, v0
	v_cmp_lt_f32_e64 s[6:7], 0, v1
	s_nop 1
	v_cndmask_b32_e64 v1, v2, v3, s[6:7]
	v_mul_f32_e32 v2, 0x37800000, v1
	v_cndmask_b32_e32 v1, v1, v2, vcc
	v_cmp_class_f32_e32 vcc, v0, v208
	s_nop 0
	s_nop 0
	v_cndmask_b32_e32 v0, v1, v0, vcc
	v_fmamk_f32 v2, v0, 0x3f8147ae, v209
	v_xor_b32_e32 v16, 0x80000000, v2
	v_add_u32_e32 v28, 0, v142
	v_add_u32_e32 v168, v28, v170
	v_lshlrev_b32_e32 v171, 1, v26
	v_lshlrev_b32_e32 v172, 1, v27
	s_waitcnt vmcnt(0)
	ds_write_b128 v168, v[92:95]
	ds_write_b128 v168, v[88:91] offset:9216
	v_add3_u32 v8, 0, v171, v172
	v_add_u32_e32 v169, v8, v170
	v_mul_lo_u32 v173, v25, s94
	v_add_u32_e32 v9, 0x4800, v169
	v_add_u32_e32 v143, v8, v173
	ds_write2_b64 v9, v[84:85], v[86:87] offset1:2
	v_add_u32_e32 v4, 0x4800, v143
	ds_write2_b64 v4, v[80:81], v[82:83] offset1:2
	v_add_co_u32_e32 v0, vcc, s65, v22
	s_mov_b32 s6, 0x102000
	s_nop 0
	v_addc_co_u32_e32 v1, vcc, 0, v23, vcc
	global_load_dwordx4 v[228:231], v[0:1], off
	v_add_co_u32_e32 v0, vcc, s6, v22
	v_lshlrev_b32_e32 v2, 4, v161
	s_nop 0
	v_addc_co_u32_e32 v1, vcc, 0, v23, vcc
	global_load_dwordx4 v[232:235], v[0:1], off
	global_load_dwordx4 v[236:239], v[20:21], off offset:128
	global_load_dwordx4 v[240:243], v[18:19], off offset:128
	v_lshl_or_b32 v0, v160, 6, v17
	v_mul_lo_u32 v175, v0, s94
	v_mad_u64_u32 v[0:1], s[6:7], s13, v219, v[36:37]
	v_and_b32_e32 v2, 0x70, v2
	v_or_b32_e32 v0, v0, v2
	v_lshl_add_u64 v[144:145], s[70:71], 0, v[0:1]
	v_mad_u64_u32 v[0:1], s[6:7], s13, v219, v[34:35]
	v_readlane_b32 s6, v248, 42
	s_add_u32 s6, s6, s11
	v_readlane_b32 s7, v248, 43
	v_or_b32_e32 v0, v0, v2
	s_addc_u32 s7, s7, 0
	v_mov_b32_e32 v17, v16
	v_mov_b32_e32 v18, v16
	v_mov_b32_e32 v19, v16
	v_mov_b32_e32 v20, v16
	v_mov_b32_e32 v21, v16
	v_mov_b32_e32 v22, v16
	v_mov_b32_e32 v23, v16
	v_mov_b32_e32 v24, v16
	v_mov_b32_e32 v25, v16
	v_mov_b32_e32 v26, v16
	v_mov_b32_e32 v27, v16
	v_mov_b32_e32 v28, v16
	v_mov_b32_e32 v29, v16
	v_mov_b32_e32 v30, v16
	v_mov_b32_e32 v31, v16
	v_lshl_add_u64 v[146:147], s[70:71], 0, v[0:1]
	v_lshl_add_u64 v[148:149], s[6:7], 0, v[32:33]
	v_mov_b32_e32 v0, 0
	v_mov_b32_e32 v1, v167
	v_mov_b32_e32 v2, v167
	v_mov_b32_e32 v3, v167
	v_mov_b32_e32 v4, v167
	v_mov_b32_e32 v5, v167
	v_mov_b32_e32 v6, v167
	v_mov_b32_e32 v7, v167
	v_mov_b32_e32 v8, v167
	v_mov_b32_e32 v9, v167
	v_mov_b32_e32 v10, v167
	v_mov_b32_e32 v11, v167
	v_mov_b32_e32 v12, v167
	v_mov_b32_e32 v13, v167
	v_mov_b32_e32 v14, v167
	v_mov_b32_e32 v15, v167
	v_mov_b32_e32 v32, 0
	v_mov_b32_e32 v33, v167
	v_mov_b32_e32 v34, v167
	v_mov_b32_e32 v35, v167
	v_mov_b32_e32 v36, v167
	v_mov_b32_e32 v37, v167
	s_waitcnt lgkmcnt(0)
	s_barrier
; #define MFMA(a, b, c) __builtin_amdgcn_mfma_f32_32x32x16_bf16((a), (b), (c), 0, 0, 0)
; DI void attn_item(const P& p, int l, int item, char* smem) {
;     ...
;     if (kt + 2 < 128) {
;       const int kn = kt + 2;
; #pragma unroll
;       for (int i = 0; i < 2; ++i) kreg[i] = *(const u32x4*)(kbase + ((size_t)i * SEQ + kn * 64) * 64 + tid * 8);
; #pragma unroll
;       for (int i = 0; i < 2; ++i) {
;         const int cid = tid + NT * i;
;         const int e = cid >> 3, kc = cid & 7;
;         vreg[i] = *(const u32x4*)(vbase + (size_t)e * VTP + kn * 64 + kc * 8);
;       }
;     }
;     __builtin_amdgcn_sched_barrier(0x38F);
;     if (kt >= 0) {
;       const u16* Kc = Ks + (kt & 1) * (256 * 72);
;       const u16* Vc = Kc + 2 * 64 * 72;
;       bf16x8 kf[8];
; #pragma unroll
;       for (int i = 0; i < 8; ++i)
;         kf[i] = *(const bf16x8*)(Kc + (c * 64 + 32 * (i & 1) + li) * 72 + 16 * (i >> 1) + 8 * g);
;       u32x4 vf[16];
; #pragma unroll
;       for (int i = 0; i < 16; ++i) {
;         const int eb = i & 3, s = (i >> 2) & 1, kb = i >> 3;
;         vf[i] = *(const u32x4*)(Vc + (32 * eb + li) * 72 + 32 * kb + 16 * s + 8 * g);
;       }
;       f32x16 S[2];
; #pragma unroll
;       for (int kb = 0; kb < 2; ++kb)
; #pragma unroll
;         for (int r = 0; r < 16; ++r) S[kb][r] = negm;
; #pragma unroll
;       for (int i = 0; i < 8; ++i) S[i & 1] = MFMA(kf[i], qf[i >> 1], S[i & 1]);
;       u32x4 pk[4];
;       float sum = 0.f;
; #pragma unroll
;       for (int ch = 0; ch < 4; ++ch) {
;         const int kb = ch >> 1, s = ch & 1;
; #pragma unroll
;         for (int j2 = 0; j2 < 4; ++j2) {
;           const float p0 = __builtin_amdgcn_exp2f(S[kb][8 * s + 2 * j2]);
;           const float p1 = __builtin_amdgcn_exp2f(S[kb][8 * s + 2 * j2 + 1]);
;           sum += p0 + p1;
;           pk[ch][j2] = pack2(p0, p1);
;         }
;       }
;       ls += sum;
; #pragma unroll
;       for (int i = 0; i < 16; ++i) {
;         const int eb = i & 3, ch = i >> 2;
;         O[eb] = MFMA(__builtin_bit_cast(bf16x8, vf[i]), __builtin_bit_cast(bf16x8, pk[ch]), O[eb]);
;       }
;     }
	v_readfirstlane_b32 s98, v148
	v_readfirstlane_b32 s99, v149
	v_readfirstlane_b32 s100, v146
	v_readfirstlane_b32 s101, v147
	v_add_u32_e32 v150, v175, v188
	v_add_u32_e32 v151, v174, v188
	v_subrev_u32_e32 v156, s98, v148
	v_subrev_u32_e32 v146, s100, v146
	v_subrev_u32_e32 v144, s100, v144
	s_sub_u32 s98, s98, 0x100000
	s_subb_u32 s99, s99, 0
	v_add_u32_e32 v148, 0x100000, v156
	v_add_u32_e32 v151, 0x4800, v151
	s_mov_b64 s[14:15], 0x2000
	v_mov_b32_e32 v190, 0
	v_mov_b32_e32 v191, 0
	v_mov_b32_e32 v196, 0
	s_movk_i32 s10, 63
	s_nop 0
	ds_read_b128 v[128:131], v150 offset:0
	ds_read_b128 v[132:135], v150 offset:32
	ds_read_b128 v[136:139], v150 offset:64
	ds_read_b128 v[152:155], v150 offset:96
	ds_read_b128 v[224:227], v150 offset:4608
	ds_read_b128 v[244:247], v150 offset:4640
	s_waitcnt lgkmcnt(4)
	v_mfma_f32_32x32x16_bf16 v[96:111], v[128:131], v[112:115], v[16:31]
	ds_read_b128 v[128:131], v150 offset:4672
	v_mfma_f32_32x32x16_bf16 v[96:111], v[132:135], v[116:119], v[96:111]
	ds_read_b128 v[132:135], v150 offset:4704
	s_waitcnt lgkmcnt(4)
	v_mfma_f32_32x32x16_bf16 v[96:111], v[136:139], v[124:127], v[96:111]
	ds_read_b128 v[136:139], v151 offset:0
	v_mfma_f32_32x32x16_bf16 v[96:111], v[152:155], v[120:123], v[96:111]
	ds_read_b128 v[152:155], v151 offset:4608
	s_waitcnt lgkmcnt(4)
	v_mfma_f32_32x32x16_bf16 v[80:95], v[224:227], v[112:115], v[16:31]
	ds_read_b128 v[224:227], v151 offset:9216
	v_mfma_f32_32x32x16_bf16 v[80:95], v[244:247], v[116:119], v[80:95]
	ds_read_b128 v[244:247], v151 offset:13824
	s_nop 6
	v_exp_f32_e32 v96, v96
	v_exp_f32_e32 v97, v97
	s_waitcnt lgkmcnt(4)
	v_mfma_f32_32x32x16_bf16 v[80:95], v[128:131], v[124:127], v[80:95]
	ds_read_b128 v[128:131], v151 offset:32
	v_exp_f32_e32 v98, v98
	v_exp_f32_e32 v99, v99
	v_exp_f32_e32 v100, v100
	v_mfma_f32_32x32x16_bf16 v[80:95], v[132:135], v[120:123], v[80:95]
	ds_read_b128 v[132:135], v151 offset:4640
	v_exp_f32_e32 v101, v101
	v_exp_f32_e32 v102, v102
	v_exp_f32_e32 v103, v103
	v_cvt_pk_bf16_f32 v176, v96, v97
	v_cvt_pk_bf16_f32 v177, v98, v99
	v_cvt_pk_bf16_f32 v178, v100, v101
	v_cvt_pk_bf16_f32 v179, v102, v103
	s_nop 0
.Lat_loop:
	s_waitcnt lgkmcnt(4)
	v_mfma_f32_32x32x16_bf16 v[64:79], v[136:139], v[176:179], v[64:79]
	ds_read_b128 v[136:139], v151 offset:9248
	v_exp_f32_e64 v104, v104
	v_exp_f32_e32 v105, v105
	v_mfma_f32_32x32x16_bf16 v[48:63], v[152:155], v[176:179], v[48:63]
	ds_read_b128 v[152:155], v151 offset:13856
	v_exp_f32_e64 v106, v106
	v_exp_f32_e32 v107, v107
	v_cvt_pk_bf16_f32 v180, v104, v105
	s_waitcnt lgkmcnt(4)
	v_mfma_f32_32x32x16_bf16 v[32:47], v[224:227], v[176:179], v[32:47]
	ds_read_b128 v[224:227], v151 offset:64
	v_exp_f32_e64 v108, v108
	v_exp_f32_e64 v109, v109
	v_cvt_pk_bf16_f32 v181, v106, v107
	v_mfma_f32_32x32x16_bf16 v[0:15], v[244:247], v[176:179], v[0:15]
	ds_read_b128 v[244:247], v151 offset:4672
	v_exp_f32_e64 v110, v110
	v_exp_f32_e64 v111, v111
	v_cvt_pk_bf16_f32 v182, v108, v109
	v_cvt_pk_bf16_f32 v183, v110, v111
	s_nop 0
	s_waitcnt lgkmcnt(4)
	v_mfma_f32_32x32x16_bf16 v[64:79], v[128:131], v[180:183], v[64:79]
	ds_read_b128 v[128:131], v151 offset:9280
	v_exp_f32_e64 v80, v80
	v_exp_f32_e64 v81, v81
	v_mfma_f32_32x32x16_bf16 v[48:63], v[132:135], v[180:183], v[48:63]
	ds_read_b128 v[132:135], v151 offset:13888
	v_exp_f32_e64 v82, v82
	v_exp_f32_e32 v83, v83
	v_cvt_pk_bf16_f32 v184, v80, v81
	s_waitcnt lgkmcnt(4)
	v_mfma_f32_32x32x16_bf16 v[32:47], v[136:139], v[180:183], v[32:47]
	ds_read_b128 v[136:139], v151 offset:96
	v_exp_f32_e64 v84, v84
	v_exp_f32_e64 v85, v85
	v_cvt_pk_bf16_f32 v185, v82, v83
	v_mfma_f32_32x32x16_bf16 v[0:15], v[152:155], v[180:183], v[0:15]
	ds_read_b128 v[152:155], v151 offset:4704
	v_exp_f32_e64 v86, v86
	v_exp_f32_e64 v87, v87
	v_cvt_pk_bf16_f32 v186, v84, v85
	v_cvt_pk_bf16_f32 v187, v86, v87
	s_nop 0
	s_waitcnt lgkmcnt(4)
	v_mfma_f32_32x32x16_bf16 v[64:79], v[224:227], v[184:187], v[64:79]
	ds_read_b128 v[224:227], v151 offset:9312
	v_exp_f32_e64 v88, v88
	v_exp_f32_e64 v89, v89
	v_mfma_f32_32x32x16_bf16 v[48:63], v[244:247], v[184:187], v[48:63]
	ds_read_b128 v[244:247], v151 offset:13920
	v_exp_f32_e64 v90, v90
	v_exp_f32_e32 v91, v91
	v_cvt_pk_bf16_f32 v192, v88, v89
	s_waitcnt lgkmcnt(4)
	v_mfma_f32_32x32x16_bf16 v[32:47], v[128:131], v[184:187], v[32:47]
	v_exp_f32_e64 v92, v92
	v_exp_f32_e32 v93, v93
	v_cvt_pk_bf16_f32 v193, v90, v91
	s_waitcnt vmcnt(0)
	ds_write_b128 v168, v[228:231] offset:36864
	ds_write_b128 v168, v[232:235] offset:46080
	v_mfma_f32_32x32x16_bf16 v[0:15], v[132:135], v[184:187], v[0:15]
	v_exp_f32_e64 v94, v94
	v_exp_f32_e32 v95, v95
	v_cvt_pk_bf16_f32 v194, v92, v93
	v_cvt_pk_bf16_f32 v195, v94, v95
	s_nop 0
	ds_write_b64 v169, v[236:237] offset:55296
	ds_write_b64 v169, v[238:239] offset:55312
	s_waitcnt lgkmcnt(6)
	v_mfma_f32_32x32x16_bf16 v[64:79], v[136:139], v[192:195], v[64:79]
	v_add_f32_e64 v167, v167, v96
	v_add_f32_e64 v190, v190, v97
	v_add_f32_e64 v191, v191, v98
	v_add_f32_e64 v196, v196, v99
	v_add_f32_e64 v167, v167, v104
	v_add_f32_e64 v190, v190, v105
	v_add_f32_e32 v191, v191, v106
	ds_write_b64 v143, v[240:241] offset:55296
	ds_write_b64 v143, v[242:243] offset:55312
	v_mfma_f32_32x32x16_bf16 v[48:63], v[152:155], v[192:195], v[48:63]
	v_add_f32_e64 v167, v167, v100
	v_add_f32_e64 v190, v190, v101
	v_add_f32_e64 v191, v191, v102
	v_add_f32_e64 v196, v196, v103
	v_add_f32_e64 v196, v196, v107
	v_add_f32_e64 v167, v167, v108
	v_add_f32_e32 v190, v190, v109
	s_waitcnt lgkmcnt(6)
	v_mfma_f32_32x32x16_bf16 v[32:47], v[224:227], v[192:195], v[32:47]
	v_add_f32_e64 v191, v191, v110
	v_add_f32_e64 v196, v196, v111
	v_add_f32_e64 v167, v167, v80
	v_add_f32_e64 v190, v190, v81
	v_add_f32_e64 v191, v191, v82
	v_add_f32_e64 v196, v196, v83
	v_add_f32_e64 v167, v167, v84
	v_mfma_f32_32x32x16_bf16 v[0:15], v[244:247], v[192:195], v[0:15]
	v_add_f32_e64 v190, v190, v85
	v_add_f32_e64 v191, v191, v86
	v_add_f32_e64 v196, v196, v87
	s_waitcnt lgkmcnt(0)
	s_barrier
; #define MFMA(a, b, c) __builtin_amdgcn_mfma_f32_32x32x16_bf16((a), (b), (c), 0, 0, 0)
; DI void attn_item(const P& p, int l, int item, char* smem) {
;     ...
;     if (kt + 2 < 128) {
;       const int kn = kt + 2;
; #pragma unroll
;       for (int i = 0; i < 2; ++i) kreg[i] = *(const u32x4*)(kbase + ((size_t)i * SEQ + kn * 64) * 64 + tid * 8);
; #pragma unroll
;       for (int i = 0; i < 2; ++i) {
;         const int cid = tid + NT * i;
;         const int e = cid >> 3, kc = cid & 7;
;         vreg[i] = *(const u32x4*)(vbase + (size_t)e * VTP + kn * 64 + kc * 8);
;       }
;     }
;     __builtin_amdgcn_sched_barrier(0x38F);
;     if (kt >= 0) {
;       const u16* Kc = Ks + (kt & 1) * (256 * 72);
;       const u16* Vc = Kc + 2 * 64 * 72;
;       bf16x8 kf[8];
; #pragma unroll
;       for (int i = 0; i < 8; ++i)
;         kf[i] = *(const bf16x8*)(Kc + (c * 64 + 32 * (i & 1) + li) * 72 + 16 * (i >> 1) + 8 * g);
;       u32x4 vf[16];
; #pragma unroll
;       for (int i = 0; i < 16; ++i) {
;         const int eb = i & 3, s = (i >> 2) & 1, kb = i >> 3;
;         vf[i] = *(const u32x4*)(Vc + (32 * eb + li) * 72 + 32 * kb + 16 * s + 8 * g);
;       }
;       f32x16 S[2];
; #pragma unroll
;       for (int kb = 0; kb < 2; ++kb)
; #pragma unroll
;         for (int r = 0; r < 16; ++r) S[kb][r] = negm;
; #pragma unroll
;       for (int i = 0; i < 8; ++i) S[i & 1] = MFMA(kf[i], qf[i >> 1], S[i & 1]);
;       u32x4 pk[4];
;       float sum = 0.f;
; #pragma unroll
;       for (int ch = 0; ch < 4; ++ch) {
;         const int kb = ch >> 1, s = ch & 1;
; #pragma unroll
;         for (int j2 = 0; j2 < 4; ++j2) {
;           const float p0 = __builtin_amdgcn_exp2f(S[kb][8 * s + 2 * j2]);
;           const float p1 = __builtin_amdgcn_exp2f(S[kb][8 * s + 2 * j2 + 1]);
;           sum += p0 + p1;
;           pk[ch][j2] = pack2(p0, p1);
;         }
;       }
;       ls += sum;
; #pragma unroll
;       for (int i = 0; i < 16; ++i) {
;         const int eb = i & 3, ch = i >> 2;
;         O[eb] = MFMA(__builtin_bit_cast(bf16x8, vf[i]), __builtin_bit_cast(bf16x8, pk[ch]), O[eb]);
;       }
;     }
;     __syncthreads();
	ds_read_b128 v[128:131], v150 offset:36864
	ds_read_b128 v[132:135], v150 offset:36896
	ds_read_b128 v[136:139], v150 offset:36928
	ds_read_b128 v[152:155], v150 offset:36960
	ds_read_b128 v[224:227], v150 offset:41472
	ds_read_b128 v[244:247], v150 offset:41504
	global_load_dwordx4 v[232:235], v148, s[98:99]
	global_load_dwordx4 v[228:231], v156, s[98:99]
	global_load_dwordx4 v[236:239], v146, s[100:101]
	global_load_dwordx4 v[240:243], v144, s[100:101]
	s_waitcnt lgkmcnt(4)
	v_mfma_f32_32x32x16_bf16 v[96:111], v[128:131], v[112:115], v[16:31]
	ds_read_b128 v[128:131], v150 offset:41536
	v_add_f32_e64 v167, v167, v88
	v_add_f32_e32 v190, v190, v89
	v_mfma_f32_32x32x16_bf16 v[96:111], v[132:135], v[116:119], v[96:111]
	ds_read_b128 v[132:135], v150 offset:41568
	v_add_f32_e64 v191, v191, v90
	v_add_f32_e32 v196, v196, v91
	s_waitcnt lgkmcnt(4)
	v_mfma_f32_32x32x16_bf16 v[96:111], v[136:139], v[124:127], v[96:111]
	ds_read_b128 v[136:139], v151 offset:36864
	v_add_f32_e64 v167, v167, v92
	v_add_f32_e64 v190, v190, v93
	v_mfma_f32_32x32x16_bf16 v[96:111], v[152:155], v[120:123], v[96:111]
	ds_read_b128 v[152:155], v151 offset:41472
	v_add_f32_e64 v191, v191, v94
	v_add_f32_e32 v196, v196, v95
	s_add_u32 s98, s98, s14
	s_addc_u32 s99, s99, s15
	s_waitcnt lgkmcnt(4)
	v_mfma_f32_32x32x16_bf16 v[80:95], v[224:227], v[112:115], v[16:31]
	ds_read_b128 v[224:227], v151 offset:46080
	s_add_u32 s100, s100, s58
	s_addc_u32 s101, s101, s59
	v_mfma_f32_32x32x16_bf16 v[80:95], v[244:247], v[116:119], v[80:95]
	ds_read_b128 v[244:247], v151 offset:50688
	s_nop 2
	v_exp_f32_e64 v96, v96
	v_exp_f32_e64 v97, v97
	s_waitcnt lgkmcnt(4)
	v_mfma_f32_32x32x16_bf16 v[80:95], v[128:131], v[124:127], v[80:95]
	ds_read_b128 v[128:131], v151 offset:36896
	v_exp_f32_e64 v98, v98
	v_exp_f32_e64 v99, v99
	v_exp_f32_e64 v100, v100
	v_mfma_f32_32x32x16_bf16 v[80:95], v[132:135], v[120:123], v[80:95]
	ds_read_b128 v[132:135], v151 offset:41504
	v_exp_f32_e64 v101, v101
	v_exp_f32_e64 v102, v102
	v_exp_f32_e64 v103, v103
	v_cvt_pk_bf16_f32 v176, v96, v97
	v_cvt_pk_bf16_f32 v177, v98, v99
	v_cvt_pk_bf16_f32 v178, v100, v101
	v_cvt_pk_bf16_f32 v179, v102, v103
	s_nop 0
	s_waitcnt lgkmcnt(4)
	v_mfma_f32_32x32x16_bf16 v[64:79], v[136:139], v[176:179], v[64:79]
	ds_read_b128 v[136:139], v151 offset:46112
	v_exp_f32_e64 v104, v104
	v_exp_f32_e64 v105, v105
	v_mfma_f32_32x32x16_bf16 v[48:63], v[152:155], v[176:179], v[48:63]
	ds_read_b128 v[152:155], v151 offset:50720
	v_exp_f32_e64 v106, v106
	v_exp_f32_e32 v107, v107
	v_cvt_pk_bf16_f32 v180, v104, v105
	s_waitcnt lgkmcnt(4)
	v_mfma_f32_32x32x16_bf16 v[32:47], v[224:227], v[176:179], v[32:47]
	ds_read_b128 v[224:227], v151 offset:36928
	v_exp_f32_e64 v108, v108
	v_exp_f32_e64 v109, v109
	v_cvt_pk_bf16_f32 v181, v106, v107
	v_mfma_f32_32x32x16_bf16 v[0:15], v[244:247], v[176:179], v[0:15]
	ds_read_b128 v[244:247], v151 offset:41536
	v_exp_f32_e64 v110, v110
	v_exp_f32_e64 v111, v111
	v_cvt_pk_bf16_f32 v182, v108, v109
	v_cvt_pk_bf16_f32 v183, v110, v111
	s_nop 0
	s_waitcnt lgkmcnt(4)
	v_mfma_f32_32x32x16_bf16 v[64:79], v[128:131], v[180:183], v[64:79]
	ds_read_b128 v[128:131], v151 offset:46144
	v_exp_f32_e64 v80, v80
	v_exp_f32_e64 v81, v81
	v_mfma_f32_32x32x16_bf16 v[48:63], v[132:135], v[180:183], v[48:63]
	ds_read_b128 v[132:135], v151 offset:50752
	v_exp_f32_e64 v82, v82
	v_exp_f32_e32 v83, v83
	v_cvt_pk_bf16_f32 v184, v80, v81
	s_waitcnt lgkmcnt(4)
	v_mfma_f32_32x32x16_bf16 v[32:47], v[136:139], v[180:183], v[32:47]
	ds_read_b128 v[136:139], v151 offset:36960
	v_exp_f32_e64 v84, v84
	v_exp_f32_e64 v85, v85
	v_cvt_pk_bf16_f32 v185, v82, v83
	v_mfma_f32_32x32x16_bf16 v[0:15], v[152:155], v[180:183], v[0:15]
	ds_read_b128 v[152:155], v151 offset:41568
	v_exp_f32_e64 v86, v86
	v_exp_f32_e64 v87, v87
	v_cvt_pk_bf16_f32 v186, v84, v85
	v_cvt_pk_bf16_f32 v187, v86, v87
	s_nop 0
	s_waitcnt lgkmcnt(4)
	v_mfma_f32_32x32x16_bf16 v[64:79], v[224:227], v[184:187], v[64:79]
	ds_read_b128 v[224:227], v151 offset:46176
	v_exp_f32_e64 v88, v88
	v_exp_f32_e64 v89, v89
	v_mfma_f32_32x32x16_bf16 v[48:63], v[244:247], v[184:187], v[48:63]
	ds_read_b128 v[244:247], v151 offset:50784
	v_exp_f32_e64 v90, v90
	v_exp_f32_e32 v91, v91
	v_cvt_pk_bf16_f32 v192, v88, v89
	s_waitcnt lgkmcnt(4)
	v_mfma_f32_32x32x16_bf16 v[32:47], v[128:131], v[184:187], v[32:47]
	v_exp_f32_e64 v92, v92
	v_exp_f32_e32 v93, v93
	v_cvt_pk_bf16_f32 v193, v90, v91
	s_waitcnt vmcnt(0)
	ds_write_b128 v168, v[228:231] offset:0
	ds_write_b128 v168, v[232:235] offset:9216
	v_mfma_f32_32x32x16_bf16 v[0:15], v[132:135], v[184:187], v[0:15]
	v_exp_f32_e64 v94, v94
	v_exp_f32_e32 v95, v95
	v_cvt_pk_bf16_f32 v194, v92, v93
	v_cvt_pk_bf16_f32 v195, v94, v95
	s_nop 0
	ds_write_b64 v169, v[236:237] offset:18432
	ds_write_b64 v169, v[238:239] offset:18448
	s_waitcnt lgkmcnt(6)
	v_mfma_f32_32x32x16_bf16 v[64:79], v[136:139], v[192:195], v[64:79]
	v_add_f32_e64 v167, v167, v96
	v_add_f32_e64 v190, v190, v97
	v_add_f32_e64 v191, v191, v98
	v_add_f32_e64 v196, v196, v99
	v_add_f32_e64 v167, v167, v104
	v_add_f32_e64 v190, v190, v105
	v_add_f32_e32 v191, v191, v106
	ds_write_b64 v143, v[240:241] offset:18432
	ds_write_b64 v143, v[242:243] offset:18448
	v_mfma_f32_32x32x16_bf16 v[48:63], v[152:155], v[192:195], v[48:63]
	v_add_f32_e64 v167, v167, v100
	v_add_f32_e64 v190, v190, v101
	v_add_f32_e64 v191, v191, v102
	v_add_f32_e64 v196, v196, v103
	v_add_f32_e64 v196, v196, v107
	v_add_f32_e64 v167, v167, v108
	v_add_f32_e32 v190, v190, v109
	s_waitcnt lgkmcnt(6)
	v_mfma_f32_32x32x16_bf16 v[32:47], v[224:227], v[192:195], v[32:47]
	v_add_f32_e64 v191, v191, v110
	v_add_f32_e64 v196, v196, v111
	v_add_f32_e64 v167, v167, v80
	v_add_f32_e64 v190, v190, v81
	v_add_f32_e64 v191, v191, v82
	v_add_f32_e64 v196, v196, v83
	v_add_f32_e64 v167, v167, v84
	v_mfma_f32_32x32x16_bf16 v[0:15], v[244:247], v[192:195], v[0:15]
	v_add_f32_e64 v190, v190, v85
	v_add_f32_e64 v191, v191, v86
	v_add_f32_e32 v196, v196, v87
	s_waitcnt lgkmcnt(0)
	s_barrier
; #define MFMA(a, b, c) __builtin_amdgcn_mfma_f32_32x32x16_bf16((a), (b), (c), 0, 0, 0)
; DI void attn_item(const P& p, int l, int item, char* smem) {
;     ...
;     if (kt + 2 < 128) {
;       const int kn = kt + 2;
; #pragma unroll
;       for (int i = 0; i < 2; ++i) kreg[i] = *(const u32x4*)(kbase + ((size_t)i * SEQ + kn * 64) * 64 + tid * 8);
; #pragma unroll
;       for (int i = 0; i < 2; ++i) {
;         const int cid = tid + NT * i;
;         const int e = cid >> 3, kc = cid & 7;
;         vreg[i] = *(const u32x4*)(vbase + (size_t)e * VTP + kn * 64 + kc * 8);
;       }
;     }
;     __builtin_amdgcn_sched_barrier(0x38F);
;     if (kt >= 0) {
;       const u16* Kc = Ks + (kt & 1) * (256 * 72);
;       const u16* Vc = Kc + 2 * 64 * 72;
;       bf16x8 kf[8];
; #pragma unroll
;       for (int i = 0; i < 8; ++i)
;         kf[i] = *(const bf16x8*)(Kc + (c * 64 + 32 * (i & 1) + li) * 72 + 16 * (i >> 1) + 8 * g);
;       u32x4 vf[16];
; #pragma unroll
;       for (int i = 0; i < 16; ++i) {
;         const int eb = i & 3, s = (i >> 2) & 1, kb = i >> 3;
;         vf[i] = *(const u32x4*)(Vc + (32 * eb + li) * 72 + 32 * kb + 16 * s + 8 * g);
;       }
;       f32x16 S[2];
; #pragma unroll
;       for (int kb = 0; kb < 2; ++kb)
; #pragma unroll
;         for (int r = 0; r < 16; ++r) S[kb][r] = negm;
; #pragma unroll
;       for (int i = 0; i < 8; ++i) S[i & 1] = MFMA(kf[i], qf[i >> 1], S[i & 1]);
;       u32x4 pk[4];
;       float sum = 0.f;
; #pragma unroll
;       for (int ch = 0; ch < 4; ++ch) {
;         const int kb = ch >> 1, s = ch & 1;
; #pragma unroll
;         for (int j2 = 0; j2 < 4; ++j2) {
;           const float p0 = __builtin_amdgcn_exp2f(S[kb][8 * s + 2 * j2]);
;           const float p1 = __builtin_amdgcn_exp2f(S[kb][8 * s + 2 * j2 + 1]);
;           sum += p0 + p1;
;           pk[ch][j2] = pack2(p0, p1);
;         }
;       }
;       ls += sum;
; #pragma unroll
;       for (int i = 0; i < 16; ++i) {
;         const int eb = i & 3, ch = i >> 2;
;         O[eb] = MFMA(__builtin_bit_cast(bf16x8, vf[i]), __builtin_bit_cast(bf16x8, pk[ch]), O[eb]);
;       }
;     }
	s_add_i32 s10, s10, -1
	s_cmp_eq_u32 s10, 0
	s_cbranch_scc1 .Lat_exit
	ds_read_b128 v[128:131], v150 offset:0
	ds_read_b128 v[132:135], v150 offset:32
	ds_read_b128 v[136:139], v150 offset:64
	ds_read_b128 v[152:155], v150 offset:96
	ds_read_b128 v[224:227], v150 offset:4608
	ds_read_b128 v[244:247], v150 offset:4640
	global_load_dwordx4 v[232:235], v148, s[98:99]
	global_load_dwordx4 v[228:231], v156, s[98:99]
	global_load_dwordx4 v[236:239], v146, s[100:101]
	global_load_dwordx4 v[240:243], v144, s[100:101]
	s_waitcnt lgkmcnt(4)
	v_mfma_f32_32x32x16_bf16 v[96:111], v[128:131], v[112:115], v[16:31]
	ds_read_b128 v[128:131], v150 offset:4672
	v_add_f32_e64 v167, v167, v88
	v_add_f32_e32 v190, v190, v89
	v_mfma_f32_32x32x16_bf16 v[96:111], v[132:135], v[116:119], v[96:111]
	ds_read_b128 v[132:135], v150 offset:4704
	v_add_f32_e64 v191, v191, v90
	v_add_f32_e32 v196, v196, v91
	s_waitcnt lgkmcnt(4)
	v_mfma_f32_32x32x16_bf16 v[96:111], v[136:139], v[124:127], v[96:111]
	ds_read_b128 v[136:139], v151 offset:0
	v_add_f32_e64 v167, v167, v92
	v_add_f32_e64 v190, v190, v93
	v_mfma_f32_32x32x16_bf16 v[96:111], v[152:155], v[120:123], v[96:111]
	ds_read_b128 v[152:155], v151 offset:4608
	v_add_f32_e64 v191, v191, v94
	v_add_f32_e32 v196, v196, v95
	s_add_u32 s98, s98, s14
	s_addc_u32 s99, s99, s15
	s_waitcnt lgkmcnt(4)
	v_mfma_f32_32x32x16_bf16 v[80:95], v[224:227], v[112:115], v[16:31]
	ds_read_b128 v[224:227], v151 offset:9216
	s_add_u32 s100, s100, s58
	s_addc_u32 s101, s101, s59
	v_mfma_f32_32x32x16_bf16 v[80:95], v[244:247], v[116:119], v[80:95]
	ds_read_b128 v[244:247], v151 offset:13824
	s_nop 2
	v_exp_f32_e64 v96, v96
	v_exp_f32_e64 v97, v97
	s_waitcnt lgkmcnt(4)
	v_mfma_f32_32x32x16_bf16 v[80:95], v[128:131], v[124:127], v[80:95]
	ds_read_b128 v[128:131], v151 offset:32
	v_exp_f32_e64 v98, v98
	v_exp_f32_e64 v99, v99
	v_exp_f32_e64 v100, v100
	v_mfma_f32_32x32x16_bf16 v[80:95], v[132:135], v[120:123], v[80:95]
	ds_read_b128 v[132:135], v151 offset:4640
	v_exp_f32_e64 v101, v101
	v_exp_f32_e64 v102, v102
	v_exp_f32_e64 v103, v103
	v_cvt_pk_bf16_f32 v176, v96, v97
	v_cvt_pk_bf16_f32 v177, v98, v99
	v_cvt_pk_bf16_f32 v178, v100, v101
	v_cvt_pk_bf16_f32 v179, v102, v103
	s_nop 0
	s_branch .Lat_loop
.Lat_exit:
	ds_read_b128 v[128:131], v150 offset:0
	ds_read_b128 v[132:135], v150 offset:32
	ds_read_b128 v[136:139], v150 offset:64
	ds_read_b128 v[152:155], v150 offset:96
	ds_read_b128 v[224:227], v150 offset:4608
	ds_read_b128 v[244:247], v150 offset:4640
	global_load_dwordx4 v[232:235], v148, s[98:99]
	global_load_dwordx4 v[228:231], v156, s[98:99]
	global_load_dwordx4 v[236:239], v146, s[100:101]
	global_load_dwordx4 v[240:243], v144, s[100:101]
	s_waitcnt lgkmcnt(4)
	v_mfma_f32_32x32x16_bf16 v[96:111], v[128:131], v[112:115], v[16:31]
	ds_read_b128 v[128:131], v150 offset:4672
	v_add_f32_e32 v167, v167, v88
	v_add_f32_e32 v190, v190, v89
	v_mfma_f32_32x32x16_bf16 v[96:111], v[132:135], v[116:119], v[96:111]
	ds_read_b128 v[132:135], v150 offset:4704
	v_add_f32_e32 v191, v191, v90
	v_add_f32_e32 v196, v196, v91
	s_waitcnt lgkmcnt(4)
	v_mfma_f32_32x32x16_bf16 v[96:111], v[136:139], v[124:127], v[96:111]
	ds_read_b128 v[136:139], v151 offset:0
	v_add_f32_e32 v167, v167, v92
	v_add_f32_e32 v190, v190, v93
	v_mfma_f32_32x32x16_bf16 v[96:111], v[152:155], v[120:123], v[96:111]
	ds_read_b128 v[152:155], v151 offset:4608
	v_add_f32_e32 v191, v191, v94
	v_add_f32_e32 v196, v196, v95
	s_add_u32 s98, s98, s14
	s_addc_u32 s99, s99, s15
	s_waitcnt lgkmcnt(4)
	v_mfma_f32_32x32x16_bf16 v[80:95], v[224:227], v[112:115], v[16:31]
	ds_read_b128 v[224:227], v151 offset:9216
	s_add_u32 s100, s100, s58
	s_addc_u32 s101, s101, s59
	v_mfma_f32_32x32x16_bf16 v[80:95], v[244:247], v[116:119], v[80:95]
	ds_read_b128 v[244:247], v151 offset:13824
	s_nop 2
	v_exp_f32_e32 v96, v96
	v_exp_f32_e32 v97, v97
	s_waitcnt lgkmcnt(4)
	v_mfma_f32_32x32x16_bf16 v[80:95], v[128:131], v[124:127], v[80:95]
	ds_read_b128 v[128:131], v151 offset:32
	v_exp_f32_e32 v98, v98
	v_exp_f32_e32 v99, v99
	v_exp_f32_e32 v100, v100
	v_mfma_f32_32x32x16_bf16 v[80:95], v[132:135], v[120:123], v[80:95]
	ds_read_b128 v[132:135], v151 offset:4640
	v_exp_f32_e32 v101, v101
	v_exp_f32_e32 v102, v102
	v_exp_f32_e32 v103, v103
	v_cvt_pk_bf16_f32 v176, v96, v97
	v_cvt_pk_bf16_f32 v177, v98, v99
	v_cvt_pk_bf16_f32 v178, v100, v101
	v_cvt_pk_bf16_f32 v179, v102, v103
	s_nop 0
	s_waitcnt lgkmcnt(4)
	v_mfma_f32_32x32x16_bf16 v[64:79], v[136:139], v[176:179], v[64:79]
	ds_read_b128 v[136:139], v151 offset:9248
	v_exp_f32_e32 v104, v104
	v_exp_f32_e32 v105, v105
	v_mfma_f32_32x32x16_bf16 v[48:63], v[152:155], v[176:179], v[48:63]
	ds_read_b128 v[152:155], v151 offset:13856
	v_exp_f32_e32 v106, v106
	v_exp_f32_e32 v107, v107
	v_cvt_pk_bf16_f32 v180, v104, v105
	s_waitcnt lgkmcnt(4)
	v_mfma_f32_32x32x16_bf16 v[32:47], v[224:227], v[176:179], v[32:47]
	ds_read_b128 v[224:227], v151 offset:64
	v_exp_f32_e32 v108, v108
	v_exp_f32_e32 v109, v109
	v_cvt_pk_bf16_f32 v181, v106, v107
	v_mfma_f32_32x32x16_bf16 v[0:15], v[244:247], v[176:179], v[0:15]
	ds_read_b128 v[244:247], v151 offset:4672
	v_exp_f32_e32 v110, v110
	v_exp_f32_e32 v111, v111
	v_cvt_pk_bf16_f32 v182, v108, v109
	v_cvt_pk_bf16_f32 v183, v110, v111
	s_nop 0
	s_waitcnt lgkmcnt(4)
	v_mfma_f32_32x32x16_bf16 v[64:79], v[128:131], v[180:183], v[64:79]
	ds_read_b128 v[128:131], v151 offset:9280
	v_exp_f32_e32 v80, v80
	v_exp_f32_e32 v81, v81
	v_mfma_f32_32x32x16_bf16 v[48:63], v[132:135], v[180:183], v[48:63]
	ds_read_b128 v[132:135], v151 offset:13888
	v_exp_f32_e32 v82, v82
	v_exp_f32_e32 v83, v83
	v_cvt_pk_bf16_f32 v184, v80, v81
	s_waitcnt lgkmcnt(4)
; #define MFMA(a, b, c) __builtin_amdgcn_mfma_f32_32x32x16_bf16((a), (b), (c), 0, 0, 0)
; DI void attn_item(const P& p, int l, int item, char* smem) {
;     ...
;     if (kt >= 0) {
;       const u16* Kc = Ks + (kt & 1) * (256 * 72);
;       const u16* Vc = Kc + 2 * 64 * 72;
;       bf16x8 kf[8];
; #pragma unroll
;       for (int i = 0; i < 8; ++i)
;         kf[i] = *(const bf16x8*)(Kc + (c * 64 + 32 * (i & 1) + li) * 72 + 16 * (i >> 1) + 8 * g);
;       u32x4 vf[16];
; #pragma unroll
;       for (int i = 0; i < 16; ++i) {
;         const int eb = i & 3, s = (i >> 2) & 1, kb = i >> 3;
;         vf[i] = *(const u32x4*)(Vc + (32 * eb + li) * 72 + 32 * kb + 16 * s + 8 * g);
;       }
;       f32x16 S[2];
; #pragma unroll
;       for (int kb = 0; kb < 2; ++kb)
; #pragma unroll
;         for (int r = 0; r < 16; ++r) S[kb][r] = negm;
; #pragma unroll
;       for (int i = 0; i < 8; ++i) S[i & 1] = MFMA(kf[i], qf[i >> 1], S[i & 1]);
;       u32x4 pk[4];
;       float sum = 0.f;
; #pragma unroll
;       for (int ch = 0; ch < 4; ++ch) {
;         const int kb = ch >> 1, s = ch & 1;
; #pragma unroll
;         for (int j2 = 0; j2 < 4; ++j2) {
;           const float p0 = __builtin_amdgcn_exp2f(S[kb][8 * s + 2 * j2]);
;           const float p1 = __builtin_amdgcn_exp2f(S[kb][8 * s + 2 * j2 + 1]);
;           sum += p0 + p1;
;           pk[ch][j2] = pack2(p0, p1);
;         }
;       }
;       ls += sum;
; #pragma unroll
;       for (int i = 0; i < 16; ++i) {
;         const int eb = i & 3, ch = i >> 2;
;         O[eb] = MFMA(__builtin_bit_cast(bf16x8, vf[i]), __builtin_bit_cast(bf16x8, pk[ch]), O[eb]);
;       }
;     }
;     __syncthreads();
	v_mfma_f32_32x32x16_bf16 v[32:47], v[136:139], v[180:183], v[32:47]
	ds_read_b128 v[136:139], v151 offset:96
	v_exp_f32_e32 v84, v84
	v_exp_f32_e32 v85, v85
	v_cvt_pk_bf16_f32 v185, v82, v83
	v_mfma_f32_32x32x16_bf16 v[0:15], v[152:155], v[180:183], v[0:15]
	ds_read_b128 v[152:155], v151 offset:4704
	v_exp_f32_e32 v86, v86
	v_exp_f32_e32 v87, v87
	v_cvt_pk_bf16_f32 v186, v84, v85
	v_cvt_pk_bf16_f32 v187, v86, v87
	s_nop 0
	s_waitcnt lgkmcnt(4)
	v_mfma_f32_32x32x16_bf16 v[64:79], v[224:227], v[184:187], v[64:79]
	ds_read_b128 v[224:227], v151 offset:9312
	v_exp_f32_e32 v88, v88
	v_exp_f32_e32 v89, v89
	v_mfma_f32_32x32x16_bf16 v[48:63], v[244:247], v[184:187], v[48:63]
	ds_read_b128 v[244:247], v151 offset:13920
	v_exp_f32_e32 v90, v90
	v_exp_f32_e32 v91, v91
	v_cvt_pk_bf16_f32 v192, v88, v89
	s_waitcnt lgkmcnt(4)
	v_mfma_f32_32x32x16_bf16 v[32:47], v[128:131], v[184:187], v[32:47]
	v_exp_f32_e32 v92, v92
	v_exp_f32_e32 v93, v93
	v_cvt_pk_bf16_f32 v193, v90, v91
	s_waitcnt vmcnt(0)
	ds_write_b128 v168, v[228:231] offset:36864
	ds_write_b128 v168, v[232:235] offset:46080
	v_mfma_f32_32x32x16_bf16 v[0:15], v[132:135], v[184:187], v[0:15]
	v_exp_f32_e32 v94, v94
	v_exp_f32_e32 v95, v95
	v_cvt_pk_bf16_f32 v194, v92, v93
	v_cvt_pk_bf16_f32 v195, v94, v95
	s_nop 0
	ds_write_b64 v169, v[236:237] offset:55296
	ds_write_b64 v169, v[238:239] offset:55312
	s_waitcnt lgkmcnt(6)
	v_mfma_f32_32x32x16_bf16 v[64:79], v[136:139], v[192:195], v[64:79]
	v_add_f32_e32 v167, v167, v96
	v_add_f32_e32 v190, v190, v97
	v_add_f32_e32 v191, v191, v98
	v_add_f32_e32 v196, v196, v99
	v_add_f32_e32 v167, v167, v104
	v_add_f32_e32 v190, v190, v105
	v_add_f32_e32 v191, v191, v106
	ds_write_b64 v143, v[240:241] offset:55296
	ds_write_b64 v143, v[242:243] offset:55312
	v_mfma_f32_32x32x16_bf16 v[48:63], v[152:155], v[192:195], v[48:63]
	v_add_f32_e32 v167, v167, v100
	v_add_f32_e32 v190, v190, v101
	v_add_f32_e32 v191, v191, v102
	v_add_f32_e32 v196, v196, v103
	v_add_f32_e32 v196, v196, v107
	v_add_f32_e32 v167, v167, v108
	v_add_f32_e32 v190, v190, v109
	s_waitcnt lgkmcnt(6)
	v_mfma_f32_32x32x16_bf16 v[32:47], v[224:227], v[192:195], v[32:47]
	v_add_f32_e32 v191, v191, v110
	v_add_f32_e32 v196, v196, v111
	v_add_f32_e32 v167, v167, v80
	v_add_f32_e32 v190, v190, v81
	v_add_f32_e32 v191, v191, v82
	v_add_f32_e32 v196, v196, v83
	v_add_f32_e32 v167, v167, v84
	v_mfma_f32_32x32x16_bf16 v[0:15], v[244:247], v[192:195], v[0:15]
	v_add_f32_e32 v190, v190, v85
	v_add_f32_e32 v191, v191, v86
	v_add_f32_e32 v196, v196, v87
	s_waitcnt lgkmcnt(0)
	s_barrier
	ds_read_b128 v[128:131], v150 offset:36864
	ds_read_b128 v[132:135], v150 offset:36896
	ds_read_b128 v[136:139], v150 offset:36928
	ds_read_b128 v[152:155], v150 offset:36960
	ds_read_b128 v[224:227], v150 offset:41472
	ds_read_b128 v[244:247], v150 offset:41504
	s_waitcnt lgkmcnt(4)
	v_mfma_f32_32x32x16_bf16 v[96:111], v[128:131], v[112:115], v[16:31]
	ds_read_b128 v[128:131], v150 offset:41536
	v_add_f32_e32 v167, v167, v88
	v_add_f32_e32 v190, v190, v89
	v_mfma_f32_32x32x16_bf16 v[96:111], v[132:135], v[116:119], v[96:111]
	ds_read_b128 v[132:135], v150 offset:41568
	v_add_f32_e32 v191, v191, v90
	v_add_f32_e32 v196, v196, v91
	s_waitcnt lgkmcnt(4)
	v_mfma_f32_32x32x16_bf16 v[96:111], v[136:139], v[124:127], v[96:111]
	ds_read_b128 v[136:139], v151 offset:36864
	v_add_f32_e32 v167, v167, v92
	v_add_f32_e32 v190, v190, v93
	v_mfma_f32_32x32x16_bf16 v[96:111], v[152:155], v[120:123], v[96:111]
	ds_read_b128 v[152:155], v151 offset:41472
	v_add_f32_e32 v191, v191, v94
	v_add_f32_e32 v196, v196, v95
	s_waitcnt lgkmcnt(4)
	v_mfma_f32_32x32x16_bf16 v[80:95], v[224:227], v[112:115], v[16:31]
	ds_read_b128 v[224:227], v151 offset:46080
	v_mfma_f32_32x32x16_bf16 v[80:95], v[244:247], v[116:119], v[80:95]
	ds_read_b128 v[244:247], v151 offset:50688
	s_nop 6
	v_exp_f32_e32 v96, v96
	v_exp_f32_e32 v97, v97
	s_waitcnt lgkmcnt(4)
	v_mfma_f32_32x32x16_bf16 v[80:95], v[128:131], v[124:127], v[80:95]
	ds_read_b128 v[128:131], v151 offset:36896
	v_exp_f32_e32 v98, v98
	v_exp_f32_e32 v99, v99
	v_exp_f32_e32 v100, v100
	v_mfma_f32_32x32x16_bf16 v[80:95], v[132:135], v[120:123], v[80:95]
	ds_read_b128 v[132:135], v151 offset:41504
	v_exp_f32_e32 v101, v101
	v_exp_f32_e32 v102, v102
	v_exp_f32_e32 v103, v103
	v_cvt_pk_bf16_f32 v176, v96, v97
	v_cvt_pk_bf16_f32 v177, v98, v99
	v_cvt_pk_bf16_f32 v178, v100, v101
	v_cvt_pk_bf16_f32 v179, v102, v103
	s_nop 0
	s_waitcnt lgkmcnt(4)
	v_mfma_f32_32x32x16_bf16 v[64:79], v[136:139], v[176:179], v[64:79]
	ds_read_b128 v[136:139], v151 offset:46112
	v_exp_f32_e32 v104, v104
	v_exp_f32_e32 v105, v105
	v_mfma_f32_32x32x16_bf16 v[48:63], v[152:155], v[176:179], v[48:63]
	ds_read_b128 v[152:155], v151 offset:50720
	v_exp_f32_e32 v106, v106
	v_exp_f32_e32 v107, v107
	v_cvt_pk_bf16_f32 v180, v104, v105
	s_waitcnt lgkmcnt(4)
	v_mfma_f32_32x32x16_bf16 v[32:47], v[224:227], v[176:179], v[32:47]
	ds_read_b128 v[224:227], v151 offset:36928
	v_exp_f32_e32 v108, v108
	v_exp_f32_e32 v109, v109
	v_cvt_pk_bf16_f32 v181, v106, v107
	v_mfma_f32_32x32x16_bf16 v[0:15], v[244:247], v[176:179], v[0:15]
	ds_read_b128 v[244:247], v151 offset:41536
	v_exp_f32_e32 v110, v110
	v_exp_f32_e32 v111, v111
	v_cvt_pk_bf16_f32 v182, v108, v109
	v_cvt_pk_bf16_f32 v183, v110, v111
	s_nop 0
	s_waitcnt lgkmcnt(4)
; #define MFMA(a, b, c) __builtin_amdgcn_mfma_f32_32x32x16_bf16((a), (b), (c), 0, 0, 0)
; DI void attn_item(const P& p, int l, int item, char* smem) {
;     ...
; #pragma unroll
;       for (int ch = 0; ch < 4; ++ch) {
;         const int kb = ch >> 1, s = ch & 1;
; #pragma unroll
;         for (int j2 = 0; j2 < 4; ++j2) {
;           const float p0 = __builtin_amdgcn_exp2f(S[kb][8 * s + 2 * j2]);
;           const float p1 = __builtin_amdgcn_exp2f(S[kb][8 * s + 2 * j2 + 1]);
;           sum += p0 + p1;
;           pk[ch][j2] = pack2(p0, p1);
;         }
;       }
;       ls += sum;
; #pragma unroll
;       for (int i = 0; i < 16; ++i) {
;         const int eb = i & 3, ch = i >> 2;
;         O[eb] = MFMA(__builtin_bit_cast(bf16x8, vf[i]), __builtin_bit_cast(bf16x8, pk[ch]), O[eb]);
;       }
;     }
;     __syncthreads();
;   }
;   const float lt = ls + __shfl_xor(ls, 32);
;   const float inv = (c == 0) ? (1.0f / lt) : (lam / lt);
;     ...
;   if (c == 0) {
;     float ss = 0.f;
; #pragma unroll
;     for (int eb = 0; eb < 4; ++eb)
; #pragma unroll
;       for (int r = 0; r < 16; ++r) {
;         const float o = O[eb][r] * inv - exch[(eb * 16 + r) * 64 + lane];
;         O[eb][r] = o;
;         ss += o * o;
;       }
;     ss += __shfl_xor(ss, 32);
;     const float rn = rsqrtf(ss * (1.0f / 128.0f) + 1e-5f) * (1.0f - lam_init);
;     const size_t tok = (size_t)b * SEQ + tq;
; #pragma unroll
;     for (int eb = 0; eb < 4; ++eb)
; #pragma unroll
;       for (int rq = 0; rq < 4; ++rq) {
;         const int e = 32 * eb + 8 * rq + 4 * g;
;         const uint2 gt = *(const uint2*)(p.AG + tok * 512 + h * 128 + e);
;         const float4 sg = *(const float4*)(p.subg + l * 128 + e);
	v_mfma_f32_32x32x16_bf16 v[64:79], v[128:131], v[180:183], v[64:79]
	ds_read_b128 v[128:131], v151 offset:46144
	v_exp_f32_e32 v80, v80
	v_exp_f32_e32 v81, v81
	v_mfma_f32_32x32x16_bf16 v[48:63], v[132:135], v[180:183], v[48:63]
	ds_read_b128 v[132:135], v151 offset:50752
	v_exp_f32_e32 v82, v82
	v_exp_f32_e32 v83, v83
	v_cvt_pk_bf16_f32 v184, v80, v81
	s_waitcnt lgkmcnt(4)
	v_mfma_f32_32x32x16_bf16 v[32:47], v[136:139], v[180:183], v[32:47]
	ds_read_b128 v[136:139], v151 offset:36960
	v_exp_f32_e32 v84, v84
	v_exp_f32_e32 v85, v85
	v_cvt_pk_bf16_f32 v185, v82, v83
	v_mfma_f32_32x32x16_bf16 v[0:15], v[152:155], v[180:183], v[0:15]
	ds_read_b128 v[152:155], v151 offset:41568
	v_exp_f32_e32 v86, v86
	v_exp_f32_e32 v87, v87
	v_cvt_pk_bf16_f32 v186, v84, v85
	v_cvt_pk_bf16_f32 v187, v86, v87
	s_nop 0
	s_waitcnt lgkmcnt(4)
	v_mfma_f32_32x32x16_bf16 v[64:79], v[224:227], v[184:187], v[64:79]
	ds_read_b128 v[224:227], v151 offset:46176
	v_exp_f32_e32 v88, v88
	v_exp_f32_e32 v89, v89
	v_mfma_f32_32x32x16_bf16 v[48:63], v[244:247], v[184:187], v[48:63]
	ds_read_b128 v[244:247], v151 offset:50784
	v_exp_f32_e32 v90, v90
	v_exp_f32_e32 v91, v91
	v_cvt_pk_bf16_f32 v192, v88, v89
	s_waitcnt lgkmcnt(4)
	v_mfma_f32_32x32x16_bf16 v[32:47], v[128:131], v[184:187], v[32:47]
	v_exp_f32_e32 v92, v92
	v_exp_f32_e32 v93, v93
	v_cvt_pk_bf16_f32 v193, v90, v91
	v_mfma_f32_32x32x16_bf16 v[0:15], v[132:135], v[184:187], v[0:15]
	v_exp_f32_e32 v94, v94
	v_exp_f32_e32 v95, v95
	v_cvt_pk_bf16_f32 v194, v92, v93
	v_cvt_pk_bf16_f32 v195, v94, v95
	s_nop 0
	s_waitcnt lgkmcnt(2)
	v_mfma_f32_32x32x16_bf16 v[64:79], v[136:139], v[192:195], v[64:79]
	v_add_f32_e32 v167, v167, v96
	v_add_f32_e32 v190, v190, v97
	v_add_f32_e32 v191, v191, v98
	v_add_f32_e32 v196, v196, v99
	v_add_f32_e32 v167, v167, v104
	v_add_f32_e32 v190, v190, v105
	v_add_f32_e32 v191, v191, v106
	v_mfma_f32_32x32x16_bf16 v[48:63], v[152:155], v[192:195], v[48:63]
	v_add_f32_e32 v167, v167, v100
	v_add_f32_e32 v190, v190, v101
	v_add_f32_e32 v191, v191, v102
	v_add_f32_e32 v196, v196, v103
	v_add_f32_e32 v196, v196, v107
	v_add_f32_e32 v167, v167, v108
	v_add_f32_e32 v190, v190, v109
	s_waitcnt lgkmcnt(0)
	v_mfma_f32_32x32x16_bf16 v[32:47], v[224:227], v[192:195], v[32:47]
	v_add_f32_e32 v191, v191, v110
	v_add_f32_e32 v196, v196, v111
	v_add_f32_e32 v167, v167, v80
	v_add_f32_e32 v190, v190, v81
	v_add_f32_e32 v191, v191, v82
	v_add_f32_e32 v196, v196, v83
	v_add_f32_e32 v167, v167, v84
	v_mfma_f32_32x32x16_bf16 v[0:15], v[244:247], v[192:195], v[0:15]
	v_add_f32_e32 v190, v190, v85
	v_add_f32_e32 v191, v191, v86
	v_add_f32_e32 v196, v196, v87
	s_waitcnt lgkmcnt(0)
	s_barrier
	v_add_f32_e32 v167, v167, v88
	v_add_f32_e32 v190, v190, v89
	v_add_f32_e32 v191, v191, v90
	v_add_f32_e32 v196, v196, v91
	v_add_f32_e32 v167, v167, v92
	v_add_f32_e32 v190, v190, v93
	v_add_f32_e32 v191, v191, v94
	v_add_f32_e32 v196, v196, v95
	v_add_f32_e32 v167, v167, v190
	v_add_f32_e32 v191, v191, v196
	v_readlane_b32 s6, v248, 5
	v_add_f32_e32 v96, v165, v166
	v_add_f32_e32 v97, v163, v164
	v_mul_f32_e32 v96, 0x3fb8aa3b, v96
	v_mul_f32_e32 v97, 0x3fb8aa3b, v97
	v_exp_f32_e32 v139, v96
	v_exp_f32_e32 v17, v97
	v_add_f32_e32 v16, v167, v191
	ds_bpermute_b32 v18, v158, v16
	v_sub_f32_e32 v17, v17, v139
	v_add_f32_e32 v17, s6, v17
	s_movk_i32 s6, 0x100
	v_cmp_gt_u32_e64 s[6:7], s6, v161
	s_waitcnt lgkmcnt(0)
	v_add_f32_e32 v16, v16, v18
	s_nop 0
	v_cndmask_b32_e64 v17, v17, 1.0, s[6:7]
	v_div_scale_f32 v18, s[10:11], v16, v16, v17
	v_rcp_f32_e32 v19, v18
	s_nop 0
	v_fma_f32 v24, -v18, v19, 1.0
	s_nop 0
	v_fmac_f32_e32 v19, v24, v19
	v_div_scale_f32 v24, vcc, v17, v16, v17
	v_mul_f32_e32 v25, v24, v19
	v_fma_f32 v26, -v18, v25, v24
	v_fmac_f32_e32 v25, v26, v19
	v_fma_f32 v18, -v18, v25, v24
	s_nop 0
	v_div_fmas_f32 v18, v18, v19, v25
	v_div_fixup_f32 v80, v18, v16, v17
	v_lshl_add_u32 v16, v162, 14, 0
	v_cmp_eq_u32_e32 vcc, 1, v160
	v_lshl_add_u32 v18, v141, 2, v16
	s_nop 0
	s_and_saveexec_b64 s[10:11], s[6:7]
	s_cbranch_execz .Lfin_nl
	v_and_b32_e32 v142, 15, v161
	v_bfe_u32 v143, v161, 4, 2
	v_and_b32_e32 v144, 0xffffffe0, v140
	v_add_u32_e32 v144, v144, v143
	s_lshl_b32 s56, s12, 11
	s_and_b32 s56, s56, 0x2000
	v_add_u32_e32 v144, s56, v144
	v_lshlrev_b32_e32 v144, 10, v144
	s_lshl_b32 s56, s95, 8
	s_and_b32 s56, s56, 0x300
	v_add_u32_e32 v144, s56, v144
	v_lshl_add_u32 v144, v142, 4, v144
	v_mov_b32_e32 v147, v144
	v_lshlrev_b32_e32 v145, 5, v142
	global_load_dwordx4 v[100:103], v145, s[30:31]
	global_load_dwordx4 v[104:107], v145, s[30:31] offset:16
	global_load_dwordx4 v[228:231], v144, s[44:45]
	v_add_u32_e32 v144, 0x1000, v144
	global_load_dwordx4 v[232:235], v144, s[44:45]
	v_add_u32_e32 v144, 0x1000, v144
	global_load_dwordx4 v[236:239], v144, s[44:45]
	v_add_u32_e32 v144, 0x1000, v144
	global_load_dwordx4 v[240:243], v144, s[44:45]
	v_add_u32_e32 v144, 0x1000, v144
	global_load_dwordx4 v[84:87], v144, s[44:45]
	v_add_u32_e32 v144, 0x1000, v144
	global_load_dwordx4 v[88:91], v144, s[44:45]
	v_add_u32_e32 v144, 0x1000, v144
	global_load_dwordx4 v[92:95], v144, s[44:45]
	v_add_u32_e32 v144, 0x1000, v144
	global_load_dwordx4 v[96:99], v144, s[44:45]
